# v31 + RWKV chunk loop: C1 first operand LDS read hoisted above stage D, stage D tail LDS reads hoisted to its start (exposed LDS latency hidden)
# speedup vs baseline: 1.0034x; 1.0034x over previous
.LBB0_1236:
	s_nop 0
	ds_read2_b64 v[218:221], v110 offset0:32 offset1:64
	s_cmp_eq_u32 s4, 0
	s_cbranch_scc1 .Lrw_skipd
	s_add_i32 s98, s4, -1
	s_xor_b32 s101, s100, 0xe100
	s_cmp_lg_u32 s100, 0
	s_cselect_b32 s97, 0, 64
	v_add_u32_e32 v166, s97, v123
	v_add_u32_e32 v165, s101, v121
	ds_read_b32 v105, v166 offset:57600
	ds_read_b64 v[222:223], v165 offset:37120
	ds_read_b128 v[56:59], v94 offset:57856
	ds_read_b128 v[60:63], v94 offset:57872
	ds_read_b128 v[64:67], v94 offset:57888
	ds_read_b128 v[68:71], v94 offset:57904
	s_waitcnt lgkmcnt(3)
	v_add_f32_e32 v56, v56, v57
	v_add_f32_e32 v57, v58, v59
	v_add_f32_e32 v56, v56, v57
	s_waitcnt lgkmcnt(2)
	v_add_f32_e32 v57, v60, v61
	v_add_f32_e32 v58, v62, v63
	v_add_f32_e32 v57, v57, v58
	v_add_f32_e32 v56, v56, v57
	s_waitcnt lgkmcnt(1)
	v_add_f32_e32 v57, v64, v65
	v_add_f32_e32 v58, v66, v67
	v_add_f32_e32 v57, v57, v58
	s_waitcnt lgkmcnt(0)
	v_add_f32_e32 v58, v68, v69
	v_add_f32_e32 v59, v70, v71
	v_add_f32_e32 v58, v58, v59
	v_add_f32_e32 v57, v57, v58
	v_add_f32_e32 v58, v56, v57
	s_nop 1
	v_add_f32_dpp v58, v58, v58 quad_perm:[1,0,3,2] row_mask:0xf bank_mask:0xf bound_ctrl:1
	s_nop 1
	v_add_f32_dpp v58, v58, v58 quad_perm:[2,3,0,1] row_mask:0xf bank_mask:0xf bound_ctrl:1
	s_nop 1
	v_add_f32_dpp v58, v58, v58 row_half_mirror row_mask:0xf bank_mask:0xf bound_ctrl:1
	s_nop 1
	v_add_f32_dpp v58, v58, v58 row_mirror row_mask:0xf bank_mask:0xf bound_ctrl:1
	s_nop 0
	v_readlane_b32 s19, v58, 16
	v_readlane_b32 s23, v58, 48
	v_readlane_b32 s18, v58, 0
	v_readlane_b32 s22, v58, 32
	v_mov_b32_e32 v58, s19
	v_mov_b32_e32 v59, s23
	v_add_f32_e32 v58, s18, v58
	v_add_f32_e32 v59, s22, v59
	v_cndmask_b32_e64 v58, v59, v58, s[12:13]
	v_fmac_f32_e32 v57, 0xbc800000, v58
	v_fmac_f32_e32 v56, 0xbc800000, v58
	v_mul_f32_e32 v58, v57, v57
	v_fmac_f32_e32 v58, v56, v56
	s_nop 1
	v_add_f32_dpp v58, v58, v58 quad_perm:[1,0,3,2] row_mask:0xf bank_mask:0xf bound_ctrl:1
	s_nop 1
	v_add_f32_dpp v58, v58, v58 quad_perm:[2,3,0,1] row_mask:0xf bank_mask:0xf bound_ctrl:1
	s_nop 1
	v_add_f32_dpp v58, v58, v58 row_half_mirror row_mask:0xf bank_mask:0xf bound_ctrl:1
	s_nop 1
	v_add_f32_dpp v58, v58, v58 row_mirror row_mask:0xf bank_mask:0xf bound_ctrl:1
	s_nop 0
	v_readlane_b32 s22, v58, 0
	v_readlane_b32 s24, v58, 16
	v_readlane_b32 s23, v58, 32
	v_readlane_b32 s25, v58, 48
	s_and_saveexec_b64 s[18:19], s[16:17]
	s_cbranch_execz .Lrw_dend
	v_mov_b32_e32 v58, s24
	v_mov_b32_e32 v59, s25
	v_add_f32_e32 v58, s22, v58
	v_add_f32_e32 v59, s23, v59
	v_cndmask_b32_e64 v58, v59, v58, s[12:13]
	v_fmamk_f32 v58, v58, 0x3c800000, v120
	v_mul_f32_e32 v59, 0x4b800000, v58
	v_cmp_gt_f32_e32 vcc, s29, v58
	s_nop 1
	v_cndmask_b32_e32 v58, v58, v59, vcc
	v_rsq_f32_e32 v60, v58
	v_mov_b32_e32 v58, v162
	v_mov_b32_e32 v59, v163
	v_mul_f32_e32 v61, 0x45800000, v60
	v_cndmask_b32_e32 v64, v60, v61, vcc
	v_mul_f32_e32 v60, v57, v64
	v_mov_b32_e32 v61, v59
	v_pk_mul_f32 v[60:61], v[104:105], v[60:61]
	v_mul_f32_e32 v56, v56, v64
	v_add_f32_e32 v57, v87, v60
	v_add_f32_e32 v57, v57, v61
	v_mul_f32_e32 v59, v223, v57
	v_mov_b32_e32 v85, v105
	v_mov_b32_e32 v57, v58
	v_pk_mul_f32 v[56:57], v[84:85], v[56:57]
	s_nop 0
	v_add_f32_e32 v56, v86, v56
	v_add_f32_e32 v56, v56, v57
	v_mul_f32_e32 v56, v222, v56
	v_cvt_pk_bf16_f32 v58, v56, v59
	v_lshl_add_u32 v56, s98, 4, v95
	v_lshl_add_u32 v56, v56, 12, v178
	global_store_dword v56, v58, s[94:95] offset:2048

.Lrw_skipd:
	s_nop 0
	s_waitcnt lgkmcnt(0)
	v_mov_b32_e32 v162, v220
	v_mov_b32_e32 v163, v221
	v_pk_mul_f32 v[60:61], v[78:79], v[218:219]
	s_nop 0
	v_pk_mul_f32 v[62:63], v[60:61], v[60:61]
	v_cvt_pkrtz_f16_f32 v58, v220, v220
	v_add_f32_e32 v62, v62, v63
	v_cvt_pkrtz_f16_f32 v59, v221, v221
	ds_write_b64 v112, v[58:59]
	v_add_f32_dpp v62, v62, v62 quad_perm:[1,0,3,2] row_mask:0xf bank_mask:0xf bound_ctrl:1
	s_nop 1
	v_add_f32_dpp v62, v62, v62 quad_perm:[2,3,0,1] row_mask:0xf bank_mask:0xf bound_ctrl:1
	s_nop 1
	v_add_f32_dpp v62, v62, v62 row_half_mirror row_mask:0xf bank_mask:0xf bound_ctrl:1
	s_nop 1
	v_add_f32_dpp v62, v62, v62 row_mirror row_mask:0xf bank_mask:0xf bound_ctrl:1
	s_nop 0
	v_readlane_b32 s19, v62, 16
	v_readlane_b32 s23, v62, 48
	v_readlane_b32 s18, v62, 0
	v_readlane_b32 s22, v62, 32
	v_mov_b32_e32 v62, s19
	v_mov_b32_e32 v63, s23
	v_add_f32_e32 v62, s18, v62
	v_add_f32_e32 v63, s22, v63
	v_cndmask_b32_e64 v62, v63, v62, s[12:13]
	v_mul_f32_e32 v63, 0x4b800000, v62
	v_cmp_gt_f32_e32 vcc, s29, v62
	s_nop 1
	v_cndmask_b32_e32 v62, v62, v63, vcc
	v_rsq_f32_e32 v64, v62
	ds_read_b64 v[58:59], v111
	ds_read_b64 v[62:63], v92 offset:33024
	v_mul_f32_e32 v65, 0x45800000, v64
	v_cndmask_b32_e32 v64, v64, v65, vcc
	v_min_f32_e32 v64, 0x5368d4a5, v64
	v_pk_mul_f32 v[60:61], v[60:61], v[64:65] op_sel_hi:[1,0]
	s_nop 0
	v_cvt_pk_f16_f32 v64, v60, v61
	s_waitcnt lgkmcnt(0)
	v_pk_mul_f32 v[60:61], v[62:63], v[60:61]
	s_nop 0
	v_cvt_pk_f16_f32 v60, v60, v61
	ds_write2st64_b32 v113, v64, v60 offset0:161 offset1:177
	v_pk_add_f32 v[60:61], v[62:63], -1.0 op_sel_hi:[1,0]
	s_nop 0
	v_pk_fma_f32 v[60:61], v[80:81], v[60:61], 1.0 op_sel_hi:[1,1,0]
	s_nop 0
	v_pk_mul_f32 v[56:57], v[218:219], v[60:61]
	v_cvt_pk_f16_f32 v61, v58, v59
	v_cvt_pk_f16_f32 v60, v56, v57
	v_mul_f32_e32 v57, v59, v57
	v_mul_f32_e32 v56, v58, v56
	v_mul_f32_e32 v57, v83, v57
	v_fmac_f32_e32 v57, v82, v56
	ds_write2st64_b32 v113, v60, v61 offset0:193 offset1:209
	s_nop 0
	v_add_f32_dpp v56, v57, v57 quad_perm:[1,0,3,2] row_mask:0xf bank_mask:0xf bound_ctrl:1
	s_nop 1
	v_add_f32_dpp v56, v56, v56 quad_perm:[2,3,0,1] row_mask:0xf bank_mask:0xf bound_ctrl:1
	s_nop 1
	v_add_f32_dpp v56, v56, v56 row_half_mirror row_mask:0xf bank_mask:0xf bound_ctrl:1
	s_nop 1
	v_add_f32_dpp v56, v56, v56 row_mirror row_mask:0xf bank_mask:0xf bound_ctrl:1
	s_nop 0
	v_readlane_b32 s22, v56, 0
	v_readlane_b32 s24, v56, 16
	v_readlane_b32 s23, v56, 32
	v_readlane_b32 s25, v56, 48
	s_and_saveexec_b64 s[18:19], s[14:15]
	s_cbranch_execz .LBB0_1238
	v_mov_b32_e32 v56, s24
	v_mov_b32_e32 v57, s25
	v_add_f32_e32 v56, s22, v56
	v_add_f32_e32 v57, s23, v57
	v_cndmask_b32_e64 v56, v57, v56, s[12:13]
	s_cmp_lg_u32 s100, 0
	s_cselect_b32 s97, 64, 0
	v_add_u32_e32 v166, s97, v123
	ds_write_b32 v166, v56 offset:57600
